# strategy 7 (v_pk_* instruction selection) in the in-proj sigmoid epilogues: paired -log2e scale and +1 packed, constant in an SGPR pair; on top of the combined version
# speedup vs baseline: 1.0064x; 1.0064x over previous
; DI unsigned pk2(float lo, float hi) { f32x2 v = {lo, hi}; bf16x2v b = __builtin_convertvector(v, bf16x2v); return __builtin_bit_cast(unsigned, b); }
; DI float sigmoidf_(float x) { return __builtin_amdgcn_rcpf(1.f + __builtin_amdgcn_exp2f(-LOG2E * x)); }
;   DI void operator()(int tok0, int feat0, f32x16 (&acc)[2][2], int r, int hh) const {
;     ...
;       } else if (seg == 3) {
; #pragma unroll
;         for (int nt = 0; nt < 2; ++nt)
; #pragma unroll
;           for (int gp = 0; gp < 2; ++gp) {
;             const int c = c0 + nt * 32 + 16 * hh + 8 * gp;
;             u32x4 o = {pk2(sigmoidf_(acc[nt][mt][8 * gp]), sigmoidf_(acc[nt][mt][8 * gp + 1])), pk2(sigmoidf_(acc[nt][mt][8 * gp + 2]), sigmoidf_(acc[nt][mt][8 * gp + 3])),
;                        pk2(sigmoidf_(acc[nt][mt][8 * gp + 4]), sigmoidf_(acc[nt][mt][8 * gp + 5])), pk2(sigmoidf_(acc[nt][mt][8 * gp + 6]), sigmoidf_(acc[nt][mt][8 * gp + 7]))};
;             *(u32x4*)(fg + (size_t)tok * 1024 + c) = o;
;             __builtin_amdgcn_sched_barrier(0);
;           }
.LBB0_119:
	v_cmp_lt_i32_e64 s[10:11], 2, v213
	s_and_saveexec_b64 s[2:3], s[10:11]
	s_xor_b64 s[26:27], exec, s[2:3]
	s_cbranch_execz .LBB0_123
	v_cmp_eq_u32_e64 s[10:11], 3, v213
	s_and_saveexec_b64 s[28:29], s[10:11]
	s_cbranch_execz .LBB0_122
	v_mul_f32_e32 v66, 0xbfb8aa3b, v50
	v_mul_f32_e32 v67, 0xbfb8aa3b, v51
	v_mul_f32_e32 v68, 0xbfb8aa3b, v52
	v_mul_f32_e32 v69, 0xbfb8aa3b, v53
	v_mul_f32_e32 v70, 0xbfb8aa3b, v54
	v_mul_f32_e32 v71, 0xbfb8aa3b, v55
	v_mul_f32_e32 v73, 0xbfb8aa3b, v56
	v_mul_f32_e32 v76, 0xbfb8aa3b, v57
	v_exp_f32_e32 v66, v66
	v_exp_f32_e32 v67, v67
	v_exp_f32_e32 v68, v68
	v_exp_f32_e32 v69, v69
	v_exp_f32_e32 v70, v70
	v_exp_f32_e32 v71, v71
	v_exp_f32_e32 v73, v73
	v_exp_f32_e32 v76, v76
	v_add_f32_e32 v66, 1.0, v66
	v_add_f32_e32 v67, 1.0, v67
	v_add_f32_e32 v68, 1.0, v68
	v_add_f32_e32 v69, 1.0, v69
	v_add_f32_e32 v70, 1.0, v70
	v_add_f32_e32 v71, 1.0, v71
	v_add_f32_e32 v73, 1.0, v73
	v_add_f32_e32 v76, 1.0, v76
	v_rcp_f32_e32 v66, v66
	v_rcp_f32_e32 v67, v67
	v_rcp_f32_e32 v68, v68
	v_rcp_f32_e32 v69, v69
	v_rcp_f32_e32 v70, v70
	v_rcp_f32_e32 v71, v71
	v_rcp_f32_e32 v73, v73
	v_rcp_f32_e32 v76, v76
	v_lshlrev_b64 v[74:75], 11, v[164:165]
	v_cvt_pk_bf16_f32 v66, v66, v67
	v_cvt_pk_bf16_f32 v67, v68, v69
	v_cvt_pk_bf16_f32 v68, v70, v71
	v_cvt_pk_bf16_f32 v69, v73, v76
	v_lshl_add_u64 v[70:71], s[20:21], 0, v[74:75]
	v_add_lshl_u32 v76, v210, v211, 1
	v_mov_b32_e32 v77, v1
	v_lshl_add_u64 v[70:71], v[70:71], 0, v[76:77]
	global_store_dwordx4 v[70:71], v[66:69], off offset:128
	s_nop 1
	s_mov_b32 s100, 0xbfb8aa3b
	v_pk_mul_f32 v[66:67], v[58:59], s[100:101] op_sel_hi:[1,0]
	v_exp_f32_e32 v66, v66
	v_exp_f32_e32 v67, v67
	s_nop 0
	v_pk_add_f32 v[66:67], v[66:67], 1.0 op_sel_hi:[1,0]
	v_rcp_f32_e32 v66, v66
	v_rcp_f32_e32 v67, v67
	s_nop 0
	v_cvt_pk_bf16_f32 v68, v66, v67
	s_mov_b32 s100, 0xbfb8aa3b
	v_pk_mul_f32 v[66:67], v[60:61], s[100:101] op_sel_hi:[1,0]
	v_exp_f32_e32 v66, v66
	v_exp_f32_e32 v67, v67
	s_nop 0
	v_pk_add_f32 v[66:67], v[66:67], 1.0 op_sel_hi:[1,0]
	v_rcp_f32_e32 v66, v66
	v_rcp_f32_e32 v67, v67
	s_nop 0
	v_cvt_pk_bf16_f32 v69, v66, v67
	s_mov_b32 s100, 0xbfb8aa3b
	v_pk_mul_f32 v[66:67], v[62:63], s[100:101] op_sel_hi:[1,0]
	v_exp_f32_e32 v66, v66
	v_exp_f32_e32 v67, v67
	s_nop 0
	v_pk_add_f32 v[66:67], v[66:67], 1.0 op_sel_hi:[1,0]
	v_rcp_f32_e32 v66, v66
	v_rcp_f32_e32 v67, v67
	s_nop 0
	v_cvt_pk_bf16_f32 v70, v66, v67
	s_mov_b32 s100, 0xbfb8aa3b
	v_pk_mul_f32 v[66:67], v[64:65], s[100:101] op_sel_hi:[1,0]
	v_exp_f32_e32 v66, v66
	v_exp_f32_e32 v67, v67
	s_nop 0
	v_pk_add_f32 v[66:67], v[66:67], 1.0 op_sel_hi:[1,0]
	v_rcp_f32_e32 v66, v66
	v_rcp_f32_e32 v67, v67
	s_nop 0
	v_cvt_pk_bf16_f32 v71, v66, v67
	v_lshl_add_u64 v[66:67], s[12:13], 0, v[74:75]
	v_lshl_add_u64 v[66:67], v[66:67], 0, v[76:77]
	v_add_co_u32_e64 v66, s[10:11], s62, v66
	s_nop 1
	v_addc_co_u32_e64 v67, s[10:11], 0, v67, s[10:11]
	global_store_dwordx4 v[66:67], v[68:71], off offset:144
	s_nop 1
	v_mul_f32_e32 v68, 0xbfb8aa3b, v34
	v_mul_f32_e32 v69, 0xbfb8aa3b, v35
	v_exp_f32_e32 v68, v68
	v_exp_f32_e32 v69, v69
	v_mul_f32_e32 v70, 0xbfb8aa3b, v37
	v_exp_f32_e32 v70, v70
	v_add_f32_e32 v68, 1.0, v68
	v_add_f32_e32 v69, 1.0, v69
	v_rcp_f32_e32 v68, v68
	v_rcp_f32_e32 v69, v69
	v_add_f32_e32 v70, 1.0, v70
	v_rcp_f32_e32 v70, v70
	v_mul_f32_e32 v71, 0xbfb8aa3b, v39
	v_cvt_pk_bf16_f32 v68, v68, v69
	v_mul_f32_e32 v69, 0xbfb8aa3b, v36
	v_exp_f32_e32 v69, v69
	v_exp_f32_e32 v71, v71
	v_mul_f32_e32 v73, 0xbfb8aa3b, v41
	v_exp_f32_e32 v73, v73
	v_add_f32_e32 v69, 1.0, v69
	v_rcp_f32_e32 v69, v69
	v_add_f32_e32 v71, 1.0, v71
	v_rcp_f32_e32 v71, v71
	v_add_f32_e32 v73, 1.0, v73
	v_cvt_pk_bf16_f32 v69, v69, v70
	v_mul_f32_e32 v70, 0xbfb8aa3b, v38
	v_exp_f32_e32 v70, v70
	v_rcp_f32_e32 v73, v73
	v_add_f32_e32 v70, 1.0, v70
	v_rcp_f32_e32 v70, v70
	s_nop 0
	v_cvt_pk_bf16_f32 v70, v70, v71
	v_mul_f32_e32 v71, 0xbfb8aa3b, v40
	v_exp_f32_e32 v71, v71
	s_nop 0
	v_add_f32_e32 v71, 1.0, v71
	v_rcp_f32_e32 v71, v71
	s_nop 0
	v_cvt_pk_bf16_f32 v71, v71, v73
	global_store_dwordx4 v[66:67], v[68:71], off offset:192
	s_nop 1
	v_mul_f32_e32 v68, 0xbfb8aa3b, v42
	v_mul_f32_e32 v69, 0xbfb8aa3b, v43
	v_exp_f32_e32 v68, v68
	v_exp_f32_e32 v69, v69
	v_mul_f32_e32 v70, 0xbfb8aa3b, v45
	v_exp_f32_e32 v70, v70
	v_add_f32_e32 v68, 1.0, v68
	v_add_f32_e32 v69, 1.0, v69
	v_rcp_f32_e32 v68, v68
	v_rcp_f32_e32 v69, v69
	v_add_f32_e32 v70, 1.0, v70
	v_rcp_f32_e32 v70, v70
	v_mul_f32_e32 v71, 0xbfb8aa3b, v47
	v_cvt_pk_bf16_f32 v68, v68, v69
	v_mul_f32_e32 v69, 0xbfb8aa3b, v44
	v_exp_f32_e32 v69, v69
	v_exp_f32_e32 v71, v71
	v_mul_f32_e32 v73, 0xbfb8aa3b, v49
	v_exp_f32_e32 v73, v73
	v_add_f32_e32 v69, 1.0, v69
	v_rcp_f32_e32 v69, v69
	v_add_f32_e32 v71, 1.0, v71
	v_rcp_f32_e32 v71, v71
	v_add_f32_e32 v73, 1.0, v73
	v_cvt_pk_bf16_f32 v69, v69, v70
	v_mul_f32_e32 v70, 0xbfb8aa3b, v46
	v_exp_f32_e32 v70, v70
	v_rcp_f32_e32 v73, v73
	v_add_f32_e32 v70, 1.0, v70
	v_rcp_f32_e32 v70, v70
	s_nop 0
	v_cvt_pk_bf16_f32 v70, v70, v71
	v_mul_f32_e32 v71, 0xbfb8aa3b, v48
	v_exp_f32_e32 v71, v71
	s_nop 0
	v_add_f32_e32 v71, 1.0, v71
	v_rcp_f32_e32 v71, v71
	s_nop 0
	v_cvt_pk_bf16_f32 v71, v71, v73
	global_store_dwordx4 v[66:67], v[68:71], off offset:208

; DI unsigned pk2(float lo, float hi) { f32x2 v = {lo, hi}; bf16x2v b = __builtin_convertvector(v, bf16x2v); return __builtin_bit_cast(unsigned, b); }
; DI float siluf_(float x) { return x * __builtin_amdgcn_rcpf(1.f + __builtin_amdgcn_exp2f(-LOG2E * x)); }
;   DI void operator()(int tok0, int feat0, f32x16 (&acc)[2][2], int r, int hh) const {
;     ...
;           if (seg == 0 || seg == 3) {
;             u32x4 o = {pk2(siluf_(v[0]), siluf_(v[1])), pk2(siluf_(v[2]), siluf_(v[3])), pk2(siluf_(v[4]), siluf_(v[5])), pk2(siluf_(v[6]), siluf_(v[7]))};
;             *(u32x4*)((seg == 0 ? aq : ag) + (size_t)tok * 512 + c) = o;
.LBB0_322:
	s_or_saveexec_b64 s[4:5], s[4:5]
	v_bfrev_b32_e32 v162, 16
	v_cndmask_b32_e64 v162, v162, 0, s[12:13]
	v_mov_b32_e32 v163, v1
	v_lshl_add_u64 v[166:167], s[16:17], 0, v[162:163]
	v_lshlrev_b32_e32 v162, 1, v216
	v_lshl_add_u64 v[164:165], v[166:167], 0, v[178:179]
	s_xor_b64 exec, exec, s[4:5]
	s_cbranch_execz .LBB0_324
	v_mul_f32_e32 v163, 0xbfb8aa3b, v114
	v_exp_f32_e32 v163, v163
	s_nop 0
	v_add_f32_e32 v163, 1.0, v163
	v_rcp_f32_e32 v168, v163
	v_mul_f32_e32 v163, 0xbfb8aa3b, v115
	v_exp_f32_e32 v163, v163
	s_nop 0
	v_add_f32_e32 v163, 1.0, v163
	v_rcp_f32_e32 v169, v163
	v_mov_b32_e32 v163, v1
	v_pk_mul_f32 v[114:115], v[114:115], v[168:169]
	s_nop 0
	v_cvt_pk_bf16_f32 v114, v114, v115
	v_mul_f32_e32 v115, 0xbfb8aa3b, v116
	v_exp_f32_e32 v115, v115
	s_nop 0
	v_add_f32_e32 v115, 1.0, v115
	v_rcp_f32_e32 v168, v115
	v_mul_f32_e32 v115, 0xbfb8aa3b, v117
	v_exp_f32_e32 v115, v115
	s_nop 0
	v_add_f32_e32 v115, 1.0, v115
	v_rcp_f32_e32 v169, v115
	s_nop 0
	v_pk_mul_f32 v[116:117], v[116:117], v[168:169]
	s_nop 0
	v_cvt_pk_bf16_f32 v115, v116, v117
	s_mov_b32 s100, 0xbfb8aa3b
	v_pk_mul_f32 v[116:117], v[118:119], s[100:101] op_sel_hi:[1,0]
	v_exp_f32_e32 v116, v116
	v_exp_f32_e32 v117, v117
	s_nop 0
	v_pk_add_f32 v[116:117], v[116:117], 1.0 op_sel_hi:[1,0]
	v_rcp_f32_e32 v116, v116
	v_rcp_f32_e32 v117, v117
	s_nop 0
	v_pk_mul_f32 v[116:117], v[118:119], v[116:117]
	s_nop 0
	v_cvt_pk_bf16_f32 v116, v116, v117
	v_mul_f32_e32 v117, 0xbfb8aa3b, v120
	v_exp_f32_e32 v117, v117
	s_nop 0
	v_add_f32_e32 v117, 1.0, v117
	v_rcp_f32_e32 v118, v117
	v_mul_f32_e32 v117, 0xbfb8aa3b, v121
	v_exp_f32_e32 v117, v117
	s_nop 0
	v_add_f32_e32 v117, 1.0, v117
	v_rcp_f32_e32 v119, v117
	s_nop 0
	v_pk_mul_f32 v[118:119], v[120:121], v[118:119]
	s_nop 0
	v_cvt_pk_bf16_f32 v117, v118, v119
	v_lshl_add_u64 v[118:119], v[164:165], 0, v[162:163]
	global_store_dwordx4 v[118:119], v[114:117], off

; DI unsigned pk2(float lo, float hi) { f32x2 v = {lo, hi}; bf16x2v b = __builtin_convertvector(v, bf16x2v); return __builtin_bit_cast(unsigned, b); }
; DI float siluf_(float x) { return x * __builtin_amdgcn_rcpf(1.f + __builtin_amdgcn_exp2f(-LOG2E * x)); }
;   DI void operator()(int tok0, int feat0, f32x16 (&acc)[2][2], int r, int hh) const {
;     ...
;           if (seg == 0 || seg == 3) {
;             u32x4 o = {pk2(siluf_(v[0]), siluf_(v[1])), pk2(siluf_(v[2]), siluf_(v[3])), pk2(siluf_(v[4]), siluf_(v[5])), pk2(siluf_(v[6]), siluf_(v[7]))};
;             *(u32x4*)((seg == 0 ? aq : ag) + (size_t)tok * 512 + c) = o;
.LBB0_334:
	s_andn2_saveexec_b64 s[4:5], s[4:5]
	s_cbranch_execz .LBB0_336
	v_mul_f32_e32 v114, 0xbfb8aa3b, v122
	v_mul_f32_e32 v115, 0xbfb8aa3b, v123
	v_exp_f32_e32 v114, v114
	v_exp_f32_e32 v115, v115
	v_mov_b32_e32 v163, v1
	v_add_f32_e32 v114, 1.0, v114
	v_add_f32_e32 v115, 1.0, v115
	v_rcp_f32_e32 v114, v114
	v_rcp_f32_e32 v115, v115
	s_nop 0
	v_pk_mul_f32 v[114:115], v[122:123], v[114:115]
	s_nop 0
	v_cvt_pk_bf16_f32 v114, v114, v115
	v_mul_f32_e32 v115, 0xbfb8aa3b, v124
	v_exp_f32_e32 v115, v115
	s_nop 0
	v_add_f32_e32 v115, 1.0, v115
	v_rcp_f32_e32 v116, v115
	v_mul_f32_e32 v115, 0xbfb8aa3b, v125
	v_exp_f32_e32 v115, v115
	s_nop 0
	v_add_f32_e32 v115, 1.0, v115
	v_rcp_f32_e32 v117, v115
	s_nop 0
	v_pk_mul_f32 v[116:117], v[124:125], v[116:117]
	s_nop 0
	v_cvt_pk_bf16_f32 v115, v116, v117
	s_mov_b32 s100, 0xbfb8aa3b
	v_pk_mul_f32 v[116:117], v[126:127], s[100:101] op_sel_hi:[1,0]
	v_exp_f32_e32 v116, v116
	v_exp_f32_e32 v117, v117
	s_nop 0
	v_pk_add_f32 v[116:117], v[116:117], 1.0 op_sel_hi:[1,0]
	v_rcp_f32_e32 v116, v116
	v_rcp_f32_e32 v117, v117
	s_nop 0
	v_pk_mul_f32 v[116:117], v[126:127], v[116:117]
	s_nop 0
	v_cvt_pk_bf16_f32 v116, v116, v117
	v_mul_f32_e32 v117, 0xbfb8aa3b, v128
	v_exp_f32_e32 v117, v117
	s_nop 0
	v_add_f32_e32 v117, 1.0, v117
	v_rcp_f32_e32 v118, v117
	v_mul_f32_e32 v117, 0xbfb8aa3b, v129
	v_exp_f32_e32 v117, v117
	s_nop 0
	v_add_f32_e32 v117, 1.0, v117
	v_rcp_f32_e32 v119, v117
	s_nop 0
	v_pk_mul_f32 v[118:119], v[128:129], v[118:119]
	s_nop 0
	v_cvt_pk_bf16_f32 v117, v118, v119
	v_lshl_add_u64 v[118:119], v[164:165], 0, v[162:163]
	global_store_dwordx4 v[118:119], v[114:117], off offset:16

; DI unsigned pk2(float lo, float hi) { f32x2 v = {lo, hi}; bf16x2v b = __builtin_convertvector(v, bf16x2v); return __builtin_bit_cast(unsigned, b); }
; DI float siluf_(float x) { return x * __builtin_amdgcn_rcpf(1.f + __builtin_amdgcn_exp2f(-LOG2E * x)); }
;   DI void operator()(int tok0, int feat0, f32x16 (&acc)[2][2], int r, int hh) const {
;     ...
;           if (seg == 0 || seg == 3) {
;             u32x4 o = {pk2(siluf_(v[0]), siluf_(v[1])), pk2(siluf_(v[2]), siluf_(v[3])), pk2(siluf_(v[4]), siluf_(v[5])), pk2(siluf_(v[6]), siluf_(v[7]))};
;             *(u32x4*)((seg == 0 ? aq : ag) + (size_t)tok * 512 + c) = o;
.LBB0_346:
	s_andn2_saveexec_b64 s[4:5], s[4:5]
	s_cbranch_execz .LBB0_348
	v_mul_f32_e32 v114, 0xbfb8aa3b, v98
	v_mul_f32_e32 v115, 0xbfb8aa3b, v99
	v_exp_f32_e32 v114, v114
	v_exp_f32_e32 v115, v115
	v_mov_b32_e32 v163, v1
	v_add_f32_e32 v114, 1.0, v114
	v_add_f32_e32 v115, 1.0, v115
	v_rcp_f32_e32 v114, v114
	v_rcp_f32_e32 v115, v115
	s_nop 0
	v_pk_mul_f32 v[98:99], v[98:99], v[114:115]
	s_nop 0
	v_cvt_pk_bf16_f32 v98, v98, v99
	v_mul_f32_e32 v99, 0xbfb8aa3b, v100
	v_exp_f32_e32 v99, v99
	s_nop 0
	v_add_f32_e32 v99, 1.0, v99
	v_rcp_f32_e32 v114, v99
	v_mul_f32_e32 v99, 0xbfb8aa3b, v101
	v_exp_f32_e32 v99, v99
	s_nop 0
	v_add_f32_e32 v99, 1.0, v99
	v_rcp_f32_e32 v115, v99
	s_nop 0
	v_pk_mul_f32 v[100:101], v[100:101], v[114:115]
	s_nop 0
	v_cvt_pk_bf16_f32 v99, v100, v101
	s_mov_b32 s100, 0xbfb8aa3b
	v_pk_mul_f32 v[100:101], v[102:103], s[100:101] op_sel_hi:[1,0]
	v_exp_f32_e32 v100, v100
	v_exp_f32_e32 v101, v101
	s_nop 0
	v_pk_add_f32 v[100:101], v[100:101], 1.0 op_sel_hi:[1,0]
	v_rcp_f32_e32 v100, v100
	v_rcp_f32_e32 v101, v101
	s_nop 0
	v_pk_mul_f32 v[100:101], v[102:103], v[100:101]
	s_nop 0
	v_cvt_pk_bf16_f32 v100, v100, v101
	v_mul_f32_e32 v101, 0xbfb8aa3b, v104
	v_exp_f32_e32 v101, v101
	s_nop 0
	v_add_f32_e32 v101, 1.0, v101
	v_rcp_f32_e32 v102, v101
	v_mul_f32_e32 v101, 0xbfb8aa3b, v105
	v_exp_f32_e32 v101, v101
	s_nop 0
	v_add_f32_e32 v101, 1.0, v101
	v_rcp_f32_e32 v103, v101
	s_nop 0
	v_pk_mul_f32 v[102:103], v[104:105], v[102:103]
	s_nop 0
	v_cvt_pk_bf16_f32 v101, v102, v103
	v_lshl_add_u64 v[102:103], v[164:165], 0, v[162:163]
	global_store_dwordx4 v[102:103], v[98:101], off offset:64

; DI unsigned pk2(float lo, float hi) { f32x2 v = {lo, hi}; bf16x2v b = __builtin_convertvector(v, bf16x2v); return __builtin_bit_cast(unsigned, b); }
; DI float siluf_(float x) { return x * __builtin_amdgcn_rcpf(1.f + __builtin_amdgcn_exp2f(-LOG2E * x)); }
;   DI void operator()(int tok0, int feat0, f32x16 (&acc)[2][2], int r, int hh) const {
;     ...
;           if (seg == 0 || seg == 3) {
;             u32x4 o = {pk2(siluf_(v[0]), siluf_(v[1])), pk2(siluf_(v[2]), siluf_(v[3])), pk2(siluf_(v[4]), siluf_(v[5])), pk2(siluf_(v[6]), siluf_(v[7]))};
;             *(u32x4*)((seg == 0 ? aq : ag) + (size_t)tok * 512 + c) = o;
.LBB0_358:
	s_andn2_saveexec_b64 s[4:5], s[4:5]
	s_cbranch_execz .LBB0_360
	v_mul_f32_e32 v98, 0xbfb8aa3b, v106
	v_mul_f32_e32 v99, 0xbfb8aa3b, v107
	v_exp_f32_e32 v98, v98
	v_exp_f32_e32 v99, v99
	v_mov_b32_e32 v163, v1
	v_add_f32_e32 v98, 1.0, v98
	v_add_f32_e32 v99, 1.0, v99
	v_rcp_f32_e32 v98, v98
	v_rcp_f32_e32 v99, v99
	s_nop 0
	v_pk_mul_f32 v[98:99], v[106:107], v[98:99]
	s_nop 0
	v_cvt_pk_bf16_f32 v98, v98, v99
	v_mul_f32_e32 v99, 0xbfb8aa3b, v108
	v_exp_f32_e32 v99, v99
	s_nop 0
	v_add_f32_e32 v99, 1.0, v99
	v_rcp_f32_e32 v100, v99
	v_mul_f32_e32 v99, 0xbfb8aa3b, v109
	v_exp_f32_e32 v99, v99
	s_nop 0
	v_add_f32_e32 v99, 1.0, v99
	v_rcp_f32_e32 v101, v99
	s_nop 0
	v_pk_mul_f32 v[100:101], v[108:109], v[100:101]
	s_nop 0
	v_cvt_pk_bf16_f32 v99, v100, v101
	s_mov_b32 s100, 0xbfb8aa3b
	v_pk_mul_f32 v[100:101], v[110:111], s[100:101] op_sel_hi:[1,0]
	v_exp_f32_e32 v100, v100
	v_exp_f32_e32 v101, v101
	s_nop 0
	v_pk_add_f32 v[100:101], v[100:101], 1.0 op_sel_hi:[1,0]
	v_rcp_f32_e32 v100, v100
	v_rcp_f32_e32 v101, v101
	s_nop 0
	v_pk_mul_f32 v[100:101], v[110:111], v[100:101]
	s_nop 0
	v_cvt_pk_bf16_f32 v100, v100, v101
	v_mul_f32_e32 v101, 0xbfb8aa3b, v112
	v_exp_f32_e32 v101, v101
	s_nop 0
	v_add_f32_e32 v101, 1.0, v101
	v_rcp_f32_e32 v102, v101
	v_mul_f32_e32 v101, 0xbfb8aa3b, v113
	v_exp_f32_e32 v101, v101
	s_nop 0
	v_add_f32_e32 v101, 1.0, v101
	v_rcp_f32_e32 v103, v101
	s_nop 0
	v_pk_mul_f32 v[102:103], v[112:113], v[102:103]
	s_nop 0
	v_cvt_pk_bf16_f32 v101, v102, v103
	v_lshl_add_u64 v[102:103], v[164:165], 0, v[162:163]
	global_store_dwordx4 v[102:103], v[98:101], off offset:80

; DI unsigned pk2(float lo, float hi) { f32x2 v = {lo, hi}; bf16x2v b = __builtin_convertvector(v, bf16x2v); return __builtin_bit_cast(unsigned, b); }
; DI float siluf_(float x) { return x * __builtin_amdgcn_rcpf(1.f + __builtin_amdgcn_exp2f(-LOG2E * x)); }
;   DI void operator()(int tok0, int feat0, f32x16 (&acc)[2][2], int r, int hh) const {
;     ...
;           if (seg == 0 || seg == 3) {
;             u32x4 o = {pk2(siluf_(v[0]), siluf_(v[1])), pk2(siluf_(v[2]), siluf_(v[3])), pk2(siluf_(v[4]), siluf_(v[5])), pk2(siluf_(v[6]), siluf_(v[7]))};
;             *(u32x4*)((seg == 0 ? aq : ag) + (size_t)tok * 512 + c) = o;
.LBB0_370:
	s_or_saveexec_b64 s[4:5], s[4:5]
	v_lshl_add_u64 v[98:99], v[166:167], 0, v[108:109]
	s_xor_b64 exec, exec, s[4:5]
	s_cbranch_execz .LBB0_372
	v_mul_f32_e32 v100, 0xbfb8aa3b, v82
	v_mul_f32_e32 v101, 0xbfb8aa3b, v83
	v_exp_f32_e32 v100, v100
	v_exp_f32_e32 v101, v101
	v_mov_b32_e32 v163, v1
	v_add_f32_e32 v100, 1.0, v100
	v_add_f32_e32 v101, 1.0, v101
	v_rcp_f32_e32 v100, v100
	v_rcp_f32_e32 v101, v101
	s_nop 0
	v_pk_mul_f32 v[82:83], v[82:83], v[100:101]
	s_nop 0
	v_cvt_pk_bf16_f32 v82, v82, v83
	v_mul_f32_e32 v83, 0xbfb8aa3b, v84
	v_exp_f32_e32 v83, v83
	s_nop 0
	v_add_f32_e32 v83, 1.0, v83
	v_rcp_f32_e32 v100, v83
	v_mul_f32_e32 v83, 0xbfb8aa3b, v85
	v_exp_f32_e32 v83, v83
	s_nop 0
	v_add_f32_e32 v83, 1.0, v83
	v_rcp_f32_e32 v101, v83
	s_nop 0
	v_pk_mul_f32 v[84:85], v[84:85], v[100:101]
	s_nop 0
	v_cvt_pk_bf16_f32 v83, v84, v85
	s_mov_b32 s100, 0xbfb8aa3b
	v_pk_mul_f32 v[84:85], v[86:87], s[100:101] op_sel_hi:[1,0]
	v_exp_f32_e32 v84, v84
	v_exp_f32_e32 v85, v85
	s_nop 0
	v_pk_add_f32 v[84:85], v[84:85], 1.0 op_sel_hi:[1,0]
	v_rcp_f32_e32 v84, v84
	v_rcp_f32_e32 v85, v85
	s_nop 0
	v_pk_mul_f32 v[84:85], v[86:87], v[84:85]
	s_nop 0
	v_cvt_pk_bf16_f32 v84, v84, v85
	v_mul_f32_e32 v85, 0xbfb8aa3b, v88
	v_exp_f32_e32 v85, v85
	s_nop 0
	v_add_f32_e32 v85, 1.0, v85
	v_rcp_f32_e32 v86, v85
	v_mul_f32_e32 v85, 0xbfb8aa3b, v89
	v_exp_f32_e32 v85, v85
	s_nop 0
	v_add_f32_e32 v85, 1.0, v85
	v_rcp_f32_e32 v87, v85
	s_nop 0
	v_pk_mul_f32 v[86:87], v[88:89], v[86:87]
	s_nop 0
	v_cvt_pk_bf16_f32 v85, v86, v87
	v_lshl_add_u64 v[86:87], v[98:99], 0, v[162:163]
	global_store_dwordx4 v[86:87], v[82:85], off

; DI unsigned pk2(float lo, float hi) { f32x2 v = {lo, hi}; bf16x2v b = __builtin_convertvector(v, bf16x2v); return __builtin_bit_cast(unsigned, b); }
; DI float siluf_(float x) { return x * __builtin_amdgcn_rcpf(1.f + __builtin_amdgcn_exp2f(-LOG2E * x)); }
;   DI void operator()(int tok0, int feat0, f32x16 (&acc)[2][2], int r, int hh) const {
;     ...
;           if (seg == 0 || seg == 3) {
;             u32x4 o = {pk2(siluf_(v[0]), siluf_(v[1])), pk2(siluf_(v[2]), siluf_(v[3])), pk2(siluf_(v[4]), siluf_(v[5])), pk2(siluf_(v[6]), siluf_(v[7]))};
;             *(u32x4*)((seg == 0 ? aq : ag) + (size_t)tok * 512 + c) = o;
.LBB0_382:
	s_andn2_saveexec_b64 s[4:5], s[4:5]
	s_cbranch_execz .LBB0_384
	v_mul_f32_e32 v82, 0xbfb8aa3b, v90
	v_mul_f32_e32 v83, 0xbfb8aa3b, v91
	v_exp_f32_e32 v82, v82
	v_exp_f32_e32 v83, v83
	v_mov_b32_e32 v163, v1
	v_add_f32_e32 v82, 1.0, v82
	v_add_f32_e32 v83, 1.0, v83
	v_rcp_f32_e32 v82, v82
	v_rcp_f32_e32 v83, v83
	s_nop 0
	v_pk_mul_f32 v[82:83], v[90:91], v[82:83]
	s_nop 0
	v_cvt_pk_bf16_f32 v82, v82, v83
	v_mul_f32_e32 v83, 0xbfb8aa3b, v92
	v_exp_f32_e32 v83, v83
	s_nop 0
	v_add_f32_e32 v83, 1.0, v83
	v_rcp_f32_e32 v84, v83
	v_mul_f32_e32 v83, 0xbfb8aa3b, v93
	v_exp_f32_e32 v83, v83
	s_nop 0
	v_add_f32_e32 v83, 1.0, v83
	v_rcp_f32_e32 v85, v83
	s_nop 0
	v_pk_mul_f32 v[84:85], v[92:93], v[84:85]
	s_nop 0
	v_cvt_pk_bf16_f32 v83, v84, v85
	s_mov_b32 s100, 0xbfb8aa3b
	v_pk_mul_f32 v[84:85], v[94:95], s[100:101] op_sel_hi:[1,0]
	v_exp_f32_e32 v84, v84
	v_exp_f32_e32 v85, v85
	s_nop 0
	v_pk_add_f32 v[84:85], v[84:85], 1.0 op_sel_hi:[1,0]
	v_rcp_f32_e32 v84, v84
	v_rcp_f32_e32 v85, v85
	s_nop 0
	v_pk_mul_f32 v[84:85], v[94:95], v[84:85]
	s_nop 0
	v_cvt_pk_bf16_f32 v84, v84, v85
	v_mul_f32_e32 v85, 0xbfb8aa3b, v96
	v_exp_f32_e32 v85, v85
	s_nop 0
	v_add_f32_e32 v85, 1.0, v85
	v_rcp_f32_e32 v86, v85
	v_mul_f32_e32 v85, 0xbfb8aa3b, v97
	v_exp_f32_e32 v85, v85
	s_nop 0
	v_add_f32_e32 v85, 1.0, v85
	v_rcp_f32_e32 v87, v85
	s_nop 0
	v_pk_mul_f32 v[86:87], v[96:97], v[86:87]
	s_nop 0
	v_cvt_pk_bf16_f32 v85, v86, v87
	v_lshl_add_u64 v[86:87], v[98:99], 0, v[162:163]
	global_store_dwordx4 v[86:87], v[82:85], off offset:16

; DI unsigned pk2(float lo, float hi) { f32x2 v = {lo, hi}; bf16x2v b = __builtin_convertvector(v, bf16x2v); return __builtin_bit_cast(unsigned, b); }
; DI float siluf_(float x) { return x * __builtin_amdgcn_rcpf(1.f + __builtin_amdgcn_exp2f(-LOG2E * x)); }
;   DI void operator()(int tok0, int feat0, f32x16 (&acc)[2][2], int r, int hh) const {
;     ...
;           if (seg == 0 || seg == 3) {
;             u32x4 o = {pk2(siluf_(v[0]), siluf_(v[1])), pk2(siluf_(v[2]), siluf_(v[3])), pk2(siluf_(v[4]), siluf_(v[5])), pk2(siluf_(v[6]), siluf_(v[7]))};
;             *(u32x4*)((seg == 0 ? aq : ag) + (size_t)tok * 512 + c) = o;
.LBB0_394:
	s_andn2_saveexec_b64 s[4:5], s[4:5]
	s_cbranch_execz .LBB0_396
	v_mul_f32_e32 v82, 0xbfb8aa3b, v66
	v_mul_f32_e32 v83, 0xbfb8aa3b, v67
	v_exp_f32_e32 v82, v82
	v_exp_f32_e32 v83, v83
	v_mov_b32_e32 v163, v1
	v_add_f32_e32 v82, 1.0, v82
	v_add_f32_e32 v83, 1.0, v83
	v_rcp_f32_e32 v82, v82
	v_rcp_f32_e32 v83, v83
	s_nop 0
	v_pk_mul_f32 v[66:67], v[66:67], v[82:83]
	s_nop 0
	v_cvt_pk_bf16_f32 v66, v66, v67
	v_mul_f32_e32 v67, 0xbfb8aa3b, v68
	v_exp_f32_e32 v67, v67
	s_nop 0
	v_add_f32_e32 v67, 1.0, v67
	v_rcp_f32_e32 v82, v67
	v_mul_f32_e32 v67, 0xbfb8aa3b, v69
	v_exp_f32_e32 v67, v67
	s_nop 0
	v_add_f32_e32 v67, 1.0, v67
	v_rcp_f32_e32 v83, v67
	s_nop 0
	v_pk_mul_f32 v[68:69], v[68:69], v[82:83]
	s_nop 0
	v_cvt_pk_bf16_f32 v67, v68, v69
	s_mov_b32 s100, 0xbfb8aa3b
	v_pk_mul_f32 v[68:69], v[70:71], s[100:101] op_sel_hi:[1,0]
	v_exp_f32_e32 v68, v68
	v_exp_f32_e32 v69, v69
	s_nop 0
	v_pk_add_f32 v[68:69], v[68:69], 1.0 op_sel_hi:[1,0]
	v_rcp_f32_e32 v68, v68
	v_rcp_f32_e32 v69, v69
	s_nop 0
	v_pk_mul_f32 v[68:69], v[70:71], v[68:69]
	s_nop 0
	v_cvt_pk_bf16_f32 v68, v68, v69
	v_mul_f32_e32 v69, 0xbfb8aa3b, v72
	v_exp_f32_e32 v69, v69
	s_nop 0
	v_add_f32_e32 v69, 1.0, v69
	v_rcp_f32_e32 v70, v69
	v_mul_f32_e32 v69, 0xbfb8aa3b, v73
	v_exp_f32_e32 v69, v69
	s_nop 0
	v_add_f32_e32 v69, 1.0, v69
	v_rcp_f32_e32 v71, v69
	s_nop 0
	v_pk_mul_f32 v[70:71], v[72:73], v[70:71]
	s_nop 0
	v_cvt_pk_bf16_f32 v69, v70, v71
	v_lshl_add_u64 v[70:71], v[98:99], 0, v[162:163]
	global_store_dwordx4 v[70:71], v[66:69], off offset:64

; DI unsigned pk2(float lo, float hi) { f32x2 v = {lo, hi}; bf16x2v b = __builtin_convertvector(v, bf16x2v); return __builtin_bit_cast(unsigned, b); }
; DI float siluf_(float x) { return x * __builtin_amdgcn_rcpf(1.f + __builtin_amdgcn_exp2f(-LOG2E * x)); }
;   DI void operator()(int tok0, int feat0, f32x16 (&acc)[2][2], int r, int hh) const {
;     ...
;           if (seg == 0 || seg == 3) {
;             u32x4 o = {pk2(siluf_(v[0]), siluf_(v[1])), pk2(siluf_(v[2]), siluf_(v[3])), pk2(siluf_(v[4]), siluf_(v[5])), pk2(siluf_(v[6]), siluf_(v[7]))};
;             *(u32x4*)((seg == 0 ? aq : ag) + (size_t)tok * 512 + c) = o;
.LBB0_406:
	s_andn2_saveexec_b64 s[4:5], s[4:5]
	s_cbranch_execz .LBB0_408
	v_mul_f32_e32 v66, 0xbfb8aa3b, v74
	v_mul_f32_e32 v67, 0xbfb8aa3b, v75
	v_exp_f32_e32 v66, v66
	v_exp_f32_e32 v67, v67
	v_mov_b32_e32 v163, v1
	v_add_f32_e32 v66, 1.0, v66
	v_add_f32_e32 v67, 1.0, v67
	v_rcp_f32_e32 v66, v66
	v_rcp_f32_e32 v67, v67
	s_nop 0
	v_pk_mul_f32 v[66:67], v[74:75], v[66:67]
	s_nop 0
	v_cvt_pk_bf16_f32 v66, v66, v67
	v_mul_f32_e32 v67, 0xbfb8aa3b, v76
	v_exp_f32_e32 v67, v67
	s_nop 0
	v_add_f32_e32 v67, 1.0, v67
	v_rcp_f32_e32 v68, v67
	v_mul_f32_e32 v67, 0xbfb8aa3b, v77
	v_exp_f32_e32 v67, v67
	s_nop 0
	v_add_f32_e32 v67, 1.0, v67
	v_rcp_f32_e32 v69, v67
	s_nop 0
	v_pk_mul_f32 v[68:69], v[76:77], v[68:69]
	s_nop 0
	v_cvt_pk_bf16_f32 v67, v68, v69
	s_mov_b32 s100, 0xbfb8aa3b
	v_pk_mul_f32 v[68:69], v[78:79], s[100:101] op_sel_hi:[1,0]
	v_exp_f32_e32 v68, v68
	v_exp_f32_e32 v69, v69
	s_nop 0
	v_pk_add_f32 v[68:69], v[68:69], 1.0 op_sel_hi:[1,0]
	v_rcp_f32_e32 v68, v68
	v_rcp_f32_e32 v69, v69
	s_nop 0
	v_pk_mul_f32 v[68:69], v[78:79], v[68:69]
	s_nop 0
	v_cvt_pk_bf16_f32 v68, v68, v69
	v_mul_f32_e32 v69, 0xbfb8aa3b, v80
	v_exp_f32_e32 v69, v69
	s_nop 0
	v_add_f32_e32 v69, 1.0, v69
	v_rcp_f32_e32 v70, v69
	v_mul_f32_e32 v69, 0xbfb8aa3b, v81
	v_exp_f32_e32 v69, v69
	s_nop 0
	v_add_f32_e32 v69, 1.0, v69
	v_rcp_f32_e32 v71, v69
	s_nop 0
	v_pk_mul_f32 v[70:71], v[80:81], v[70:71]
	s_nop 0
	v_cvt_pk_bf16_f32 v69, v70, v71
	v_lshl_add_u64 v[70:71], v[98:99], 0, v[162:163]
	global_store_dwordx4 v[70:71], v[66:69], off offset:80

; DI unsigned pk2(float lo, float hi) { f32x2 v = {lo, hi}; bf16x2v b = __builtin_convertvector(v, bf16x2v); return __builtin_bit_cast(unsigned, b); }
; DI float siluf_(float x) { return x * __builtin_amdgcn_rcpf(1.f + __builtin_amdgcn_exp2f(-LOG2E * x)); }
;   DI void operator()(int tok0, int feat0, f32x16 (&acc)[2][2], int r, int hh) const {
;     ...
;           if (seg == 0 || seg == 3) {
;             u32x4 o = {pk2(siluf_(v[0]), siluf_(v[1])), pk2(siluf_(v[2]), siluf_(v[3])), pk2(siluf_(v[4]), siluf_(v[5])), pk2(siluf_(v[6]), siluf_(v[7]))};
;             *(u32x4*)((seg == 0 ? aq : ag) + (size_t)tok * 512 + c) = o;
.LBB0_418:
	s_andn2_saveexec_b64 s[4:5], s[4:5]
	s_cbranch_execz .LBB0_420
	v_mul_f32_e32 v66, 0xbfb8aa3b, v50
	v_mul_f32_e32 v67, 0xbfb8aa3b, v51
	v_exp_f32_e32 v66, v66
	v_exp_f32_e32 v67, v67
	v_mov_b32_e32 v163, v1
	v_add_f32_e32 v66, 1.0, v66
	v_add_f32_e32 v67, 1.0, v67
	v_rcp_f32_e32 v66, v66
	v_rcp_f32_e32 v67, v67
	s_nop 0
	v_pk_mul_f32 v[50:51], v[50:51], v[66:67]
	s_nop 0
	v_cvt_pk_bf16_f32 v50, v50, v51
	v_mul_f32_e32 v51, 0xbfb8aa3b, v52
	v_exp_f32_e32 v51, v51
	s_nop 0
	v_add_f32_e32 v51, 1.0, v51
	v_rcp_f32_e32 v66, v51
	v_mul_f32_e32 v51, 0xbfb8aa3b, v53
	v_exp_f32_e32 v51, v51
	s_nop 0
	v_add_f32_e32 v51, 1.0, v51
	v_rcp_f32_e32 v67, v51
	s_nop 0
	v_pk_mul_f32 v[52:53], v[52:53], v[66:67]
	s_nop 0
	v_cvt_pk_bf16_f32 v51, v52, v53
	s_mov_b32 s100, 0xbfb8aa3b
	v_pk_mul_f32 v[52:53], v[54:55], s[100:101] op_sel_hi:[1,0]
	v_exp_f32_e32 v52, v52
	v_exp_f32_e32 v53, v53
	s_nop 0
	v_pk_add_f32 v[52:53], v[52:53], 1.0 op_sel_hi:[1,0]
	v_rcp_f32_e32 v52, v52
	v_rcp_f32_e32 v53, v53
	s_nop 0
	v_pk_mul_f32 v[52:53], v[54:55], v[52:53]
	s_nop 0
	v_cvt_pk_bf16_f32 v52, v52, v53
	v_mul_f32_e32 v53, 0xbfb8aa3b, v56
	v_exp_f32_e32 v53, v53
	s_nop 0
	v_add_f32_e32 v53, 1.0, v53
	v_rcp_f32_e32 v54, v53
	v_mul_f32_e32 v53, 0xbfb8aa3b, v57
	v_exp_f32_e32 v53, v53
	s_nop 0
	v_add_f32_e32 v53, 1.0, v53
	v_rcp_f32_e32 v55, v53
	s_nop 0
	v_pk_mul_f32 v[54:55], v[56:57], v[54:55]
	s_nop 0
	v_cvt_pk_bf16_f32 v53, v54, v55
	v_lshl_add_u64 v[54:55], v[164:165], 0, v[162:163]
	global_store_dwordx4 v[54:55], v[50:53], off offset:128

; DI unsigned pk2(float lo, float hi) { f32x2 v = {lo, hi}; bf16x2v b = __builtin_convertvector(v, bf16x2v); return __builtin_bit_cast(unsigned, b); }
; DI float siluf_(float x) { return x * __builtin_amdgcn_rcpf(1.f + __builtin_amdgcn_exp2f(-LOG2E * x)); }
;   DI void operator()(int tok0, int feat0, f32x16 (&acc)[2][2], int r, int hh) const {
;     ...
;           if (seg == 0 || seg == 3) {
;             u32x4 o = {pk2(siluf_(v[0]), siluf_(v[1])), pk2(siluf_(v[2]), siluf_(v[3])), pk2(siluf_(v[4]), siluf_(v[5])), pk2(siluf_(v[6]), siluf_(v[7]))};
;             *(u32x4*)((seg == 0 ? aq : ag) + (size_t)tok * 512 + c) = o;
.LBB0_430:
	s_andn2_saveexec_b64 s[4:5], s[4:5]
	s_cbranch_execz .LBB0_432
	v_mul_f32_e32 v50, 0xbfb8aa3b, v58
	v_mul_f32_e32 v51, 0xbfb8aa3b, v59
	v_exp_f32_e32 v50, v50
	v_exp_f32_e32 v51, v51
	v_mov_b32_e32 v163, v1
	v_add_f32_e32 v50, 1.0, v50
	v_add_f32_e32 v51, 1.0, v51
	v_rcp_f32_e32 v50, v50
	v_rcp_f32_e32 v51, v51
	s_nop 0
	v_pk_mul_f32 v[50:51], v[58:59], v[50:51]
	s_nop 0
	v_cvt_pk_bf16_f32 v50, v50, v51
	v_mul_f32_e32 v51, 0xbfb8aa3b, v60
	v_exp_f32_e32 v51, v51
	s_nop 0
	v_add_f32_e32 v51, 1.0, v51
	v_rcp_f32_e32 v52, v51
	v_mul_f32_e32 v51, 0xbfb8aa3b, v61
	v_exp_f32_e32 v51, v51
	s_nop 0
	v_add_f32_e32 v51, 1.0, v51
	v_rcp_f32_e32 v53, v51
	s_nop 0
	v_pk_mul_f32 v[52:53], v[60:61], v[52:53]
	s_nop 0
	v_cvt_pk_bf16_f32 v51, v52, v53
	s_mov_b32 s100, 0xbfb8aa3b
	v_pk_mul_f32 v[52:53], v[62:63], s[100:101] op_sel_hi:[1,0]
	v_exp_f32_e32 v52, v52
	v_exp_f32_e32 v53, v53
	s_nop 0
	v_pk_add_f32 v[52:53], v[52:53], 1.0 op_sel_hi:[1,0]
	v_rcp_f32_e32 v52, v52
	v_rcp_f32_e32 v53, v53
	s_nop 0
	v_pk_mul_f32 v[52:53], v[62:63], v[52:53]
	s_nop 0
	v_cvt_pk_bf16_f32 v52, v52, v53
	v_mul_f32_e32 v53, 0xbfb8aa3b, v64
	v_exp_f32_e32 v53, v53
	s_nop 0
	v_add_f32_e32 v53, 1.0, v53
	v_rcp_f32_e32 v54, v53
	v_mul_f32_e32 v53, 0xbfb8aa3b, v65
	v_exp_f32_e32 v53, v53
	s_nop 0
	v_add_f32_e32 v53, 1.0, v53
	v_rcp_f32_e32 v55, v53
	s_nop 0
	v_pk_mul_f32 v[54:55], v[64:65], v[54:55]
	s_nop 0
	v_cvt_pk_bf16_f32 v53, v54, v55
	v_lshl_add_u64 v[54:55], v[164:165], 0, v[162:163]
	global_store_dwordx4 v[54:55], v[50:53], off offset:144

; DI unsigned pk2(float lo, float hi) { f32x2 v = {lo, hi}; bf16x2v b = __builtin_convertvector(v, bf16x2v); return __builtin_bit_cast(unsigned, b); }
; DI float siluf_(float x) { return x * __builtin_amdgcn_rcpf(1.f + __builtin_amdgcn_exp2f(-LOG2E * x)); }
;   DI void operator()(int tok0, int feat0, f32x16 (&acc)[2][2], int r, int hh) const {
;     ...
;           if (seg == 0 || seg == 3) {
;             u32x4 o = {pk2(siluf_(v[0]), siluf_(v[1])), pk2(siluf_(v[2]), siluf_(v[3])), pk2(siluf_(v[4]), siluf_(v[5])), pk2(siluf_(v[6]), siluf_(v[7]))};
;             *(u32x4*)((seg == 0 ? aq : ag) + (size_t)tok * 512 + c) = o;
.LBB0_442:
	s_andn2_saveexec_b64 s[4:5], s[4:5]
	s_cbranch_execz .LBB0_444
	v_mul_f32_e32 v50, 0xbfb8aa3b, v34
	v_mul_f32_e32 v51, 0xbfb8aa3b, v35
	v_exp_f32_e32 v50, v50
	v_exp_f32_e32 v51, v51
	v_mov_b32_e32 v163, v1
	v_add_f32_e32 v50, 1.0, v50
	v_add_f32_e32 v51, 1.0, v51
	v_rcp_f32_e32 v50, v50
	v_rcp_f32_e32 v51, v51
	s_nop 0
	v_pk_mul_f32 v[34:35], v[34:35], v[50:51]
	s_nop 0
	v_cvt_pk_bf16_f32 v34, v34, v35
	v_mul_f32_e32 v35, 0xbfb8aa3b, v36
	v_exp_f32_e32 v35, v35
	s_nop 0
	v_add_f32_e32 v35, 1.0, v35
	v_rcp_f32_e32 v50, v35
	v_mul_f32_e32 v35, 0xbfb8aa3b, v37
	v_exp_f32_e32 v35, v35
	s_nop 0
	v_add_f32_e32 v35, 1.0, v35
	v_rcp_f32_e32 v51, v35
	s_nop 0
	v_pk_mul_f32 v[36:37], v[36:37], v[50:51]
	s_nop 0
	v_cvt_pk_bf16_f32 v35, v36, v37
	s_mov_b32 s100, 0xbfb8aa3b
	v_pk_mul_f32 v[36:37], v[38:39], s[100:101] op_sel_hi:[1,0]
	v_exp_f32_e32 v36, v36
	v_exp_f32_e32 v37, v37
	s_nop 0
	v_pk_add_f32 v[36:37], v[36:37], 1.0 op_sel_hi:[1,0]
	v_rcp_f32_e32 v36, v36
	v_rcp_f32_e32 v37, v37
	s_nop 0
	v_pk_mul_f32 v[36:37], v[38:39], v[36:37]
	s_nop 0
	v_cvt_pk_bf16_f32 v36, v36, v37
	v_mul_f32_e32 v37, 0xbfb8aa3b, v40
	v_exp_f32_e32 v37, v37
	s_nop 0
	v_add_f32_e32 v37, 1.0, v37
	v_rcp_f32_e32 v38, v37
	v_mul_f32_e32 v37, 0xbfb8aa3b, v41
	v_exp_f32_e32 v37, v37
	s_nop 0
	v_add_f32_e32 v37, 1.0, v37
	v_rcp_f32_e32 v39, v37
	s_nop 0
	v_pk_mul_f32 v[38:39], v[40:41], v[38:39]
	s_nop 0
	v_cvt_pk_bf16_f32 v37, v38, v39
	v_lshl_add_u64 v[38:39], v[164:165], 0, v[162:163]
	global_store_dwordx4 v[38:39], v[34:37], off offset:192

; DI unsigned pk2(float lo, float hi) { f32x2 v = {lo, hi}; bf16x2v b = __builtin_convertvector(v, bf16x2v); return __builtin_bit_cast(unsigned, b); }
; DI float siluf_(float x) { return x * __builtin_amdgcn_rcpf(1.f + __builtin_amdgcn_exp2f(-LOG2E * x)); }
;   DI void operator()(int tok0, int feat0, f32x16 (&acc)[2][2], int r, int hh) const {
;     ...
;           if (seg == 0 || seg == 3) {
;             u32x4 o = {pk2(siluf_(v[0]), siluf_(v[1])), pk2(siluf_(v[2]), siluf_(v[3])), pk2(siluf_(v[4]), siluf_(v[5])), pk2(siluf_(v[6]), siluf_(v[7]))};
;             *(u32x4*)((seg == 0 ? aq : ag) + (size_t)tok * 512 + c) = o;
.LBB0_454:
	s_andn2_saveexec_b64 s[4:5], s[4:5]
	s_cbranch_execz .LBB0_456
	v_mul_f32_e32 v34, 0xbfb8aa3b, v42
	v_mul_f32_e32 v35, 0xbfb8aa3b, v43
	v_exp_f32_e32 v34, v34
	v_exp_f32_e32 v35, v35
	v_mov_b32_e32 v163, v1
	v_add_f32_e32 v34, 1.0, v34
	v_add_f32_e32 v35, 1.0, v35
	v_rcp_f32_e32 v34, v34
	v_rcp_f32_e32 v35, v35
	s_nop 0
	v_pk_mul_f32 v[34:35], v[42:43], v[34:35]
	s_nop 0
	v_cvt_pk_bf16_f32 v34, v34, v35
	v_mul_f32_e32 v35, 0xbfb8aa3b, v44
	v_exp_f32_e32 v35, v35
	s_nop 0
	v_add_f32_e32 v35, 1.0, v35
	v_rcp_f32_e32 v36, v35
	v_mul_f32_e32 v35, 0xbfb8aa3b, v45
	v_exp_f32_e32 v35, v35
	s_nop 0
	v_add_f32_e32 v35, 1.0, v35
	v_rcp_f32_e32 v37, v35
	s_nop 0
	v_pk_mul_f32 v[36:37], v[44:45], v[36:37]
	s_nop 0
	v_cvt_pk_bf16_f32 v35, v36, v37
	s_mov_b32 s100, 0xbfb8aa3b
	v_pk_mul_f32 v[36:37], v[46:47], s[100:101] op_sel_hi:[1,0]
	v_exp_f32_e32 v36, v36
	v_exp_f32_e32 v37, v37
	s_nop 0
	v_pk_add_f32 v[36:37], v[36:37], 1.0 op_sel_hi:[1,0]
	v_rcp_f32_e32 v36, v36
	v_rcp_f32_e32 v37, v37
	s_nop 0
	v_pk_mul_f32 v[36:37], v[46:47], v[36:37]
	s_nop 0
	v_cvt_pk_bf16_f32 v36, v36, v37
	v_mul_f32_e32 v37, 0xbfb8aa3b, v48
	v_exp_f32_e32 v37, v37
	s_nop 0
	v_add_f32_e32 v37, 1.0, v37
	v_rcp_f32_e32 v38, v37
	v_mul_f32_e32 v37, 0xbfb8aa3b, v49
	v_exp_f32_e32 v37, v37
	s_nop 0
	v_add_f32_e32 v37, 1.0, v37
	v_rcp_f32_e32 v39, v37
	s_nop 0
	v_pk_mul_f32 v[38:39], v[48:49], v[38:39]
	s_nop 0
	v_cvt_pk_bf16_f32 v37, v38, v39
	v_lshl_add_u64 v[38:39], v[164:165], 0, v[162:163]
	global_store_dwordx4 v[38:39], v[34:37], off offset:208

; DI unsigned pk2(float lo, float hi) { f32x2 v = {lo, hi}; bf16x2v b = __builtin_convertvector(v, bf16x2v); return __builtin_bit_cast(unsigned, b); }
; DI float siluf_(float x) { return x * __builtin_amdgcn_rcpf(1.f + __builtin_amdgcn_exp2f(-LOG2E * x)); }
;   DI void operator()(int tok0, int feat0, f32x16 (&acc)[2][2], int r, int hh) const {
;     ...
;           if (seg == 0 || seg == 3) {
;             u32x4 o = {pk2(siluf_(v[0]), siluf_(v[1])), pk2(siluf_(v[2]), siluf_(v[3])), pk2(siluf_(v[4]), siluf_(v[5])), pk2(siluf_(v[6]), siluf_(v[7]))};
;             *(u32x4*)((seg == 0 ? aq : ag) + (size_t)tok * 512 + c) = o;
.LBB0_466:
	s_andn2_saveexec_b64 s[4:5], s[4:5]
	s_cbranch_execz .LBB0_468
	v_mul_f32_e32 v34, 0xbfb8aa3b, v18
	v_mul_f32_e32 v35, 0xbfb8aa3b, v19
	v_exp_f32_e32 v34, v34
	v_exp_f32_e32 v35, v35
	v_mov_b32_e32 v163, v1
	v_add_f32_e32 v34, 1.0, v34
	v_add_f32_e32 v35, 1.0, v35
	v_rcp_f32_e32 v34, v34
	v_rcp_f32_e32 v35, v35
	s_nop 0
	v_pk_mul_f32 v[18:19], v[18:19], v[34:35]
	s_nop 0
	v_cvt_pk_bf16_f32 v18, v18, v19
	v_mul_f32_e32 v19, 0xbfb8aa3b, v20
	v_exp_f32_e32 v19, v19
	s_nop 0
	v_add_f32_e32 v19, 1.0, v19
	v_rcp_f32_e32 v34, v19
	v_mul_f32_e32 v19, 0xbfb8aa3b, v21
	v_exp_f32_e32 v19, v19
	s_nop 0
	v_add_f32_e32 v19, 1.0, v19
	v_rcp_f32_e32 v35, v19
	s_nop 0
	v_pk_mul_f32 v[20:21], v[20:21], v[34:35]
	s_nop 0
	v_cvt_pk_bf16_f32 v19, v20, v21
	s_mov_b32 s100, 0xbfb8aa3b
	v_pk_mul_f32 v[20:21], v[22:23], s[100:101] op_sel_hi:[1,0]
	v_exp_f32_e32 v20, v20
	v_exp_f32_e32 v21, v21
	s_nop 0
	v_pk_add_f32 v[20:21], v[20:21], 1.0 op_sel_hi:[1,0]
	v_rcp_f32_e32 v20, v20
	v_rcp_f32_e32 v21, v21
	s_nop 0
	v_pk_mul_f32 v[20:21], v[22:23], v[20:21]
	s_nop 0
	v_cvt_pk_bf16_f32 v20, v20, v21
	v_mul_f32_e32 v21, 0xbfb8aa3b, v24
	v_exp_f32_e32 v21, v21
	s_nop 0
	v_add_f32_e32 v21, 1.0, v21
	v_rcp_f32_e32 v22, v21
	v_mul_f32_e32 v21, 0xbfb8aa3b, v25
	v_exp_f32_e32 v21, v21
	s_nop 0
	v_add_f32_e32 v21, 1.0, v21
	v_rcp_f32_e32 v23, v21
	s_nop 0
	v_pk_mul_f32 v[22:23], v[24:25], v[22:23]
	s_nop 0
	v_cvt_pk_bf16_f32 v21, v22, v23
	v_lshl_add_u64 v[22:23], v[98:99], 0, v[162:163]
	global_store_dwordx4 v[22:23], v[18:21], off offset:128

; DI unsigned pk2(float lo, float hi) { f32x2 v = {lo, hi}; bf16x2v b = __builtin_convertvector(v, bf16x2v); return __builtin_bit_cast(unsigned, b); }
; DI float siluf_(float x) { return x * __builtin_amdgcn_rcpf(1.f + __builtin_amdgcn_exp2f(-LOG2E * x)); }
;   DI void operator()(int tok0, int feat0, f32x16 (&acc)[2][2], int r, int hh) const {
;     ...
;           if (seg == 0 || seg == 3) {
;             u32x4 o = {pk2(siluf_(v[0]), siluf_(v[1])), pk2(siluf_(v[2]), siluf_(v[3])), pk2(siluf_(v[4]), siluf_(v[5])), pk2(siluf_(v[6]), siluf_(v[7]))};
;             *(u32x4*)((seg == 0 ? aq : ag) + (size_t)tok * 512 + c) = o;
.LBB0_478:
	s_andn2_saveexec_b64 s[4:5], s[4:5]
	s_cbranch_execz .LBB0_480
	v_mul_f32_e32 v18, 0xbfb8aa3b, v26
	v_mul_f32_e32 v19, 0xbfb8aa3b, v27
	v_exp_f32_e32 v18, v18
	v_exp_f32_e32 v19, v19
	v_mov_b32_e32 v163, v1
	v_add_f32_e32 v18, 1.0, v18
	v_add_f32_e32 v19, 1.0, v19
	v_rcp_f32_e32 v18, v18
	v_rcp_f32_e32 v19, v19
	s_nop 0
	v_pk_mul_f32 v[18:19], v[26:27], v[18:19]
	s_nop 0
	v_cvt_pk_bf16_f32 v18, v18, v19
	v_mul_f32_e32 v19, 0xbfb8aa3b, v28
	v_exp_f32_e32 v19, v19
	s_nop 0
	v_add_f32_e32 v19, 1.0, v19
	v_rcp_f32_e32 v20, v19
	v_mul_f32_e32 v19, 0xbfb8aa3b, v29
	v_exp_f32_e32 v19, v19
	s_nop 0
	v_add_f32_e32 v19, 1.0, v19
	v_rcp_f32_e32 v21, v19
	s_nop 0
	v_pk_mul_f32 v[20:21], v[28:29], v[20:21]
	s_nop 0
	v_cvt_pk_bf16_f32 v19, v20, v21
	s_mov_b32 s100, 0xbfb8aa3b
	v_pk_mul_f32 v[20:21], v[30:31], s[100:101] op_sel_hi:[1,0]
	v_exp_f32_e32 v20, v20
	v_exp_f32_e32 v21, v21
	s_nop 0
	v_pk_add_f32 v[20:21], v[20:21], 1.0 op_sel_hi:[1,0]
	v_rcp_f32_e32 v20, v20
	v_rcp_f32_e32 v21, v21
	s_nop 0
	v_pk_mul_f32 v[20:21], v[30:31], v[20:21]
	s_nop 0
	v_cvt_pk_bf16_f32 v20, v20, v21
	v_mul_f32_e32 v21, 0xbfb8aa3b, v32
	v_exp_f32_e32 v21, v21
	s_nop 0
	v_add_f32_e32 v21, 1.0, v21
	v_rcp_f32_e32 v22, v21
	v_mul_f32_e32 v21, 0xbfb8aa3b, v33
	v_exp_f32_e32 v21, v21
	s_nop 0
	v_add_f32_e32 v21, 1.0, v21
	v_rcp_f32_e32 v23, v21
	s_nop 0
	v_pk_mul_f32 v[22:23], v[32:33], v[22:23]
	s_nop 0
	v_cvt_pk_bf16_f32 v21, v22, v23
	v_lshl_add_u64 v[22:23], v[98:99], 0, v[162:163]
	global_store_dwordx4 v[22:23], v[18:21], off offset:144

; DI unsigned pk2(float lo, float hi) { f32x2 v = {lo, hi}; bf16x2v b = __builtin_convertvector(v, bf16x2v); return __builtin_bit_cast(unsigned, b); }
; DI float siluf_(float x) { return x * __builtin_amdgcn_rcpf(1.f + __builtin_amdgcn_exp2f(-LOG2E * x)); }
;   DI void operator()(int tok0, int feat0, f32x16 (&acc)[2][2], int r, int hh) const {
;     ...
;           if (seg == 0 || seg == 3) {
;             u32x4 o = {pk2(siluf_(v[0]), siluf_(v[1])), pk2(siluf_(v[2]), siluf_(v[3])), pk2(siluf_(v[4]), siluf_(v[5])), pk2(siluf_(v[6]), siluf_(v[7]))};
;             *(u32x4*)((seg == 0 ? aq : ag) + (size_t)tok * 512 + c) = o;
.LBB0_490:
	s_andn2_saveexec_b64 s[4:5], s[4:5]
	s_cbranch_execz .LBB0_492
	v_mul_f32_e32 v18, 0xbfb8aa3b, v2
	v_mul_f32_e32 v19, 0xbfb8aa3b, v3
	v_exp_f32_e32 v18, v18
	v_exp_f32_e32 v19, v19
	v_mov_b32_e32 v163, v1
	v_add_f32_e32 v18, 1.0, v18
	v_add_f32_e32 v19, 1.0, v19
	v_rcp_f32_e32 v18, v18
	v_rcp_f32_e32 v19, v19
	s_nop 0
	v_pk_mul_f32 v[2:3], v[2:3], v[18:19]
	s_nop 0
	v_cvt_pk_bf16_f32 v2, v2, v3
	v_mul_f32_e32 v3, 0xbfb8aa3b, v4
	v_exp_f32_e32 v3, v3
	s_nop 0
	v_add_f32_e32 v3, 1.0, v3
	v_rcp_f32_e32 v18, v3
	v_mul_f32_e32 v3, 0xbfb8aa3b, v5
	v_exp_f32_e32 v3, v3
	s_nop 0
	v_add_f32_e32 v3, 1.0, v3
	v_rcp_f32_e32 v19, v3
	s_nop 0
	v_pk_mul_f32 v[4:5], v[4:5], v[18:19]
	s_nop 0
	v_cvt_pk_bf16_f32 v3, v4, v5
	s_mov_b32 s100, 0xbfb8aa3b
	v_pk_mul_f32 v[4:5], v[6:7], s[100:101] op_sel_hi:[1,0]
	v_exp_f32_e32 v4, v4
	v_exp_f32_e32 v5, v5
	s_nop 0
	v_pk_add_f32 v[4:5], v[4:5], 1.0 op_sel_hi:[1,0]
	v_rcp_f32_e32 v4, v4
	v_rcp_f32_e32 v5, v5
	s_nop 0
	v_pk_mul_f32 v[4:5], v[6:7], v[4:5]
	s_nop 0
	v_cvt_pk_bf16_f32 v4, v4, v5
	v_mul_f32_e32 v5, 0xbfb8aa3b, v8
	v_exp_f32_e32 v5, v5
	s_nop 0
	v_add_f32_e32 v5, 1.0, v5
	v_rcp_f32_e32 v6, v5
	v_mul_f32_e32 v5, 0xbfb8aa3b, v9
	v_exp_f32_e32 v5, v5
	s_nop 0
	v_add_f32_e32 v5, 1.0, v5
	v_rcp_f32_e32 v7, v5
	s_nop 0
	v_pk_mul_f32 v[6:7], v[8:9], v[6:7]
	s_nop 0
	v_cvt_pk_bf16_f32 v5, v6, v7
	v_lshl_add_u64 v[6:7], v[98:99], 0, v[162:163]
	global_store_dwordx4 v[6:7], v[2:5], off offset:192
